# v74 + GEMM phase prologue stages K-tile 1 before the first wait (vmcnt 2 -> 8): both K-tiles' first-touch loads in flight together at every phase start
# baseline (speedup 1.0000x reference)
.LBB0_183:
	v_bfe_u32 v16, v11, 4, 2
	v_and_b32_e32 v15, 15, v11
	v_lshlrev_b32_e32 v152, 4, v16
	v_lshlrev_b32_e32 v11, 2, v11
	s_and_b32 s65, s2, 3
	v_lshl_or_b32 v175, s3, 6, v15
	v_lshl_or_b32 v15, v15, 6, v152
	s_lshl_b32 s2, s3, 13
	v_and_b32_e32 v11, 32, v11
	v_bitop3_b32 v17, v15, s2, v11 bitop3:0xde
	s_lshl_b32 s7, s65, 5
	s_lshl_b32 s2, s65, 12
	s_add_u32 s74, s14, 0x17400000
	s_addc_u32 s75, s15, 0
	s_add_u32 s76, s14, 0x18cc0000
	s_addc_u32 s77, s15, 0
	s_add_u32 s62, s14, 0x19d40000
	s_addc_u32 s63, s15, 0
	v_bitop3_b32 v177, v15, s2, v11 bitop3:0xde
	s_add_u32 s2, s14, 0x1adc0000
	s_addc_u32 s3, s15, 0
	s_add_u32 s60, s14, 0x1be40000
	v_writelane_b32 v254, s2, 58
	s_addc_u32 s61, s15, 0
	s_mov_b64 s[88:89], 0x80
	v_writelane_b32 v254, s3, 59
	s_add_u32 s2, s14, 0x1cec0000
	s_addc_u32 s3, s15, 0
	s_add_u32 s86, s14, 0x29b48000
	s_addc_u32 s87, s15, 0
	s_add_i32 m0, s27, 0x18000
	v_lshl_add_u64 v[4:5], v[4:5], 0, s[88:89]
	v_writelane_b32 v254, s2, 60
	global_load_lds_dwordx4 v[4:5], off
	v_lshl_add_u64 v[2:3], v[2:3], 0, s[88:89]
	s_add_i32 m0, s27, 0x1a000
	s_add_i32 s80, s27, 0x8000
	s_add_i32 s81, s27, 0xa000
	v_writelane_b32 v254, s3, 61
	global_load_lds_dwordx4 v[2:3], off
	v_lshl_add_u64 v[0:1], v[0:1], 0, s[88:89]
	s_mov_b32 m0, s80
	s_add_u32 s2, s0, 0x80080
	global_load_lds_dwordx4 v[0:1], off
	v_lshl_add_u64 v[0:1], v[6:7], 0, s[88:89]
	s_mov_b32 m0, s81
	s_addc_u32 s3, s1, 0
	global_load_lds_dwordx4 v[0:1], off
	s_add_i32 m0, s27, 0x1c000
	v_lshl_add_u64 v[0:1], s[2:3], 0, v[146:147]
	global_load_lds_dwordx4 v[0:1], off
	v_lshl_add_u64 v[0:1], s[2:3], 0, v[150:151]
	s_add_i32 m0, s27, 0x1e000
	v_cmp_eq_u32_e64 s[2:3], 0, v16
	global_load_lds_dwordx4 v[0:1], off
	s_waitcnt vmcnt(8)
	s_barrier
	s_cmpk_lt_u32 s6, 0x100
	v_writelane_b32 v254, s2, 62
	s_cselect_b64 s[90:91], -1, 0
	s_lshl_b32 s82, s65, 6
	v_writelane_b32 v254, s3, 63
	s_ashr_i32 s83, s22, 31
	s_ashr_i32 s78, s20, 31
	s_lshl_b32 s2, s65, 7
	v_lshlrev_b32_e32 v154, 3, v16
	s_add_u32 s2, s14, s2
	v_or_b32_e32 v0, s7, v154
	s_addc_u32 s3, s15, 0
	v_or_b32_e32 v179, 0xffffe600, v0
	v_or_b32_e32 v156, s82, v154
	v_lshl_add_u64 v[0:1], s[2:3], 0, v[152:153]
	s_mov_b64 s[2:3], 0x188a0000
	v_lshl_add_u64 v[158:159], v[0:1], 0, s[2:3]
	s_mov_b64 s[2:3], 0x18480000
	v_lshlrev_b32_e32 v152, 2, v156
	v_lshl_add_u64 v[160:161], v[0:1], 0, s[2:3]
	v_lshl_add_u64 v[0:1], s[68:69], 0, v[152:153]
	s_mov_b64 s[2:3], 0x4350000
	v_lshl_add_u64 v[162:163], v[0:1], 0, s[2:3]
	s_mov_b64 s[2:3], 0x4310000
	v_lshl_add_u64 v[164:165], v[0:1], 0, s[2:3]
	v_lshlrev_b32_e32 v0, 15, v12
	v_and_b32_e32 v0, 0xffff0000, v0
	v_lshl_add_u32 v0, v13, 12, v0
	v_and_b32_e32 v1, 1, v12
	v_lshl_or_b32 v0, v1, 6, v0
	v_lshl_add_u32 v166, v14, 1, v0
	v_lshlrev_b32_e32 v0, 15, v8
	s_add_u32 s67, s68, 0x4200000
	v_and_b32_e32 v0, 0xffff0000, v0
	s_waitcnt vmcnt(6)
	s_addc_u32 s21, s69, 0
	v_lshl_add_u32 v0, v9, 12, v0
	v_and_b32_e32 v1, 1, v8
	s_add_u32 s94, s68, 0x4100000
	v_lshl_or_b32 v0, v1, 6, v0
	s_mov_b32 s66, s7
	s_mov_b32 s93, 0
	s_mov_b32 s95, s22
	s_addc_u32 s72, s69, 0
	v_mov_b32_e32 v167, v153
	v_lshl_add_u32 v168, v10, 1, v0
	v_mov_b32_e32 v169, v153
	v_mov_b64_e32 v[170:171], 0x672
	v_mov_b64_e32 v[172:173], 0x671
	s_add_i32 s73, 16, 0x10000
	s_add_i32 s54, 16, 0x14000
	v_add_u32_e32 v181, 16, v17
	v_mov_b32_e32 v187, 0x358637bd
	s_mov_b32 s55, 0x800000
	v_mbcnt_hi_u32_b32 v189, -1, v185
	v_mov_b32_e32 v202, 0x3e000000
	s_mov_b32 s79, 0
	v_mov_b32_e32 v174, v153
	v_mov_b32_e32 v176, v153
	v_mov_b32_e32 v178, v153
	v_mov_b32_e32 v180, v153
	v_mov_b32_e32 v182, v153
	v_mov_b32_e32 v184, v153
	v_mov_b32_e32 v186, v153
	v_mov_b32_e32 v188, v153
	s_barrier
	s_branch .LBB0_186

.LBB0_522:
	s_lshl_b32 s11, s11, 5
	s_and_b32 s11, s11, 0x60
	s_add_i32 m0, s63, 0x18000
	v_lshl_add_u64 v[6:7], v[6:7], 0, s[54:55]
	s_lshl_b32 s12, s10, 13
	s_lshl_b32 s24, s11, 7
	global_load_lds_dwordx4 v[6:7], off
	v_lshl_add_u64 v[4:5], v[4:5], 0, s[54:55]
	s_add_i32 m0, s63, 0x1a000
	s_add_i32 s67, s63, 0x8000
	s_add_i32 s77, s63, 0xa000
	global_load_lds_dwordx4 v[4:5], off
	v_lshl_add_u64 v[0:1], v[0:1], 0, s[54:55]
	s_mov_b32 m0, s67
	s_add_u32 s14, s94, 0x40080
	global_load_lds_dwordx4 v[0:1], off
	v_lshl_add_u64 v[0:1], v[2:3], 0, s[54:55]
	s_mov_b32 m0, s77
	s_addc_u32 s15, s95, 0
	global_load_lds_dwordx4 v[0:1], off
	s_add_i32 m0, s63, 0x1c000
	v_lshl_add_u64 v[0:1], s[14:15], 0, v[144:145]
	global_load_lds_dwordx4 v[0:1], off
	v_lshl_add_u64 v[0:1], s[14:15], 0, v[146:147]
	s_add_i32 m0, s63, 0x1e000
	s_cmpk_lt_u32 s8, 0x100
	global_load_lds_dwordx4 v[0:1], off
	s_waitcnt vmcnt(8)
	s_barrier
	v_lshrrev_b32_e32 v1, 1, v11
	v_and_b32_e32 v1, 24, v1
	v_and_b32_e32 v0, 15, v11
	v_lshlrev_b32_e32 v2, 1, v1
	v_lshl_or_b32 v152, s10, 6, v0
	v_lshl_or_b32 v0, v0, 6, v2
	v_lshlrev_b32_e32 v2, 2, v11
	v_and_b32_e32 v2, 32, v2
	v_bitop3_b32 v4, v0, s12, v2 bitop3:0xde
	v_bitop3_b32 v184, v0, s24, v2 bitop3:0xde
	v_or_b32_e32 v0, 16, v152
	v_or_b32_e32 v186, s11, v1
	v_ashrrev_i32_e32 v1, 31, v0
	v_lshlrev_b64 v[156:157], 13, v[0:1]
	v_or_b32_e32 v0, 32, v152
	v_ashrrev_i32_e32 v1, 31, v0
	v_lshlrev_b64 v[158:159], 13, v[0:1]
	v_or_b32_e32 v0, 48, v152
	v_ashrrev_i32_e32 v1, 31, v0
	v_add_u32_e32 v2, 0x2000, v152
	v_lshlrev_b64 v[160:161], 13, v[0:1]
	v_mov_b64_e32 v[0:1], s[0:1]
	s_cselect_b64 s[80:81], -1, 0
	v_add_u32_e32 v5, 0x2010, v152
	s_lshl_b32 s8, s76, 11
	v_mad_i64_i32 v[2:3], s[14:15], v2, s13, v[0:1]
	v_add_u32_e32 v6, 0x2020, v152
	v_add_u32_e32 v7, 0x2030, v152
	v_lshl_add_u64 v[162:163], v[2:3], 0, s[8:9]
	v_mad_i64_i32 v[2:3], s[14:15], v5, s13, v[0:1]
	v_lshl_add_u64 v[164:165], v[2:3], 0, s[8:9]
	v_mad_i64_i32 v[2:3], s[14:15], v6, s13, v[0:1]
	v_mad_i64_i32 v[0:1], s[14:15], v7, s13, v[0:1]
	v_lshl_add_u64 v[168:169], v[0:1], 0, s[8:9]
	v_lshlrev_b32_e32 v0, 14, v8
	v_and_b32_e32 v0, 0xffff8000, v0
	v_lshl_add_u32 v0, v9, 11, v0
	v_and_b32_e32 v1, 1, v8
	v_lshl_or_b32 v0, v1, 6, v0
	v_lshl_add_u32 v170, v10, 1, v0
	v_lshlrev_b32_e32 v0, 14, v13
	v_and_b32_e32 v0, 0xffff8000, v0
	s_waitcnt vmcnt(6)
	s_cmp_lg_u32 s76, 0
	v_lshl_add_u32 v0, v12, 11, v0
	v_and_b32_e32 v1, 1, v13
	v_ashrrev_i32_e32 v153, 31, v152
	s_cselect_b64 s[82:83], -1, 0
	s_add_u32 s84, s0, s8
	v_lshl_or_b32 v0, v1, 6, v0
	v_lshlrev_b64 v[154:155], 13, v[152:153]
	s_mov_b32 s11, 0
	s_addc_u32 s85, s1, 0
	s_lshl_b32 s56, s76, 2
	v_lshl_add_u64 v[166:167], v[2:3], 0, s[8:9]
	v_mov_b32_e32 v171, v145
	v_lshl_add_u32 v172, v14, 1, v0
	v_mov_b32_e32 v173, v145
	v_add_u32_e32 v153, 16, v4
	s_mov_b32 s12, s44
	s_mov_b32 s10, s40
	s_mov_b32 s57, s42
	s_mov_b32 s8, s43
	s_barrier
	s_branch .LBB0_525

.LBB0_614:
	v_and_b32_e32 v15, 15, v14
	s_lshl_b32 s17, s17, 5
	v_lshl_or_b32 v136, s16, 6, v15
	s_lshl_b32 s26, s16, 13
	s_and_b32 s27, s17, 0x60
	s_mov_b64 s[16:17], 0x80
	s_add_i32 m0, s11, 0x18000
	v_lshl_add_u64 v[6:7], v[6:7], 0, s[16:17]
	s_lshl_b32 s31, s27, 7
	global_load_lds_dwordx4 v[6:7], off
	v_lshl_add_u64 v[4:5], v[4:5], 0, s[16:17]
	s_add_i32 m0, s11, 0x1a000
	s_add_i32 s57, s11, 0x8000
	s_add_i32 s58, s11, 0xa000
	global_load_lds_dwordx4 v[4:5], off
	v_lshl_add_u64 v[0:1], v[0:1], 0, s[16:17]
	s_mov_b32 m0, s57
	s_add_u32 s24, s8, 0x40080
	global_load_lds_dwordx4 v[0:1], off
	v_lshl_add_u64 v[0:1], v[2:3], 0, s[16:17]
	s_mov_b32 m0, s58
	s_addc_u32 s25, s9, 0
	global_load_lds_dwordx4 v[0:1], off
	s_add_i32 m0, s11, 0x1c000
	v_lshl_add_u64 v[0:1], s[24:25], 0, v[130:131]
	global_load_lds_dwordx4 v[0:1], off
	v_lshl_add_u64 v[0:1], s[24:25], 0, v[134:135]
	s_add_i32 m0, s11, 0x1e000
	v_add_u32_e32 v3, 0x2000, v136
	global_load_lds_dwordx4 v[0:1], off
	s_waitcnt vmcnt(8)
	s_barrier
	v_or_b32_e32 v0, 16, v136
	v_ashrrev_i32_e32 v1, 31, v0
	v_lshlrev_b64 v[140:141], 13, v[0:1]
	v_or_b32_e32 v0, 32, v136
	v_ashrrev_i32_e32 v1, 31, v0
	v_lshlrev_b64 v[142:143], 13, v[0:1]
	v_or_b32_e32 v0, 48, v136
	v_ashrrev_i32_e32 v1, 31, v0
	v_add_u32_e32 v4, 0x2010, v136
	v_add_u32_e32 v5, 0x2020, v136
	v_add_u32_e32 v6, 0x2030, v136
	v_lshlrev_b64 v[144:145], 13, v[0:1]
	s_movk_i32 s63, 0x1800
	v_mov_b64_e32 v[0:1], s[0:1]
	s_sext_i32_i8 s59, s6
	s_cmpk_lt_u32 s7, 0x100
	v_mad_i64_i32 v[146:147], s[6:7], v3, s63, v[0:1]
	v_mad_i64_i32 v[148:149], s[6:7], v4, s63, v[0:1]
	v_mad_i64_i32 v[150:151], s[6:7], v5, s63, v[0:1]
	v_mad_i64_i32 v[152:153], s[6:7], v6, s63, v[0:1]
	v_lshlrev_b32_e32 v0, 14, v11
	v_and_b32_e32 v0, 0xffff8000, v0
	v_lshl_add_u32 v0, v12, 11, v0
	v_and_b32_e32 v1, 1, v11
	v_lshrrev_b32_e32 v16, 1, v14
	v_lshl_or_b32 v0, v1, 6, v0
	v_and_b32_e32 v16, 24, v16
	v_lshl_add_u32 v154, v13, 1, v0
	v_lshlrev_b32_e32 v0, 14, v8
	v_lshlrev_b32_e32 v17, 1, v16
	v_lshlrev_b32_e32 v14, 2, v14
	v_and_b32_e32 v0, 0xffff8000, v0
	v_lshl_or_b32 v15, v15, 6, v17
	v_and_b32_e32 v14, 32, v14
	s_waitcnt vmcnt(6)
	s_cselect_b64 s[34:35], -1, 0
	s_cmpk_lt_i32 s20, 0x60
	v_lshl_add_u32 v0, v9, 11, v0
	v_and_b32_e32 v1, 1, v8
	v_bitop3_b32 v175, v15, s31, v14 bitop3:0xde
	v_bitop3_b32 v2, v15, s26, v14 bitop3:0xde
	v_ashrrev_i32_e32 v137, 31, v136
	s_cselect_b64 s[52:53], -1, 0
	s_bfe_u32 s61, s20, 0x20003
	s_mov_b32 s55, 0
	v_lshl_or_b32 v0, v1, 6, v0
	s_add_i32 s64, 16, 0x10000
	s_add_i32 s65, 16, 0x14000
	v_or_b32_e32 v176, s27, v16
	v_lshlrev_b64 v[138:139], 13, v[136:137]
	s_ashr_i32 s60, s20, 5
	s_lshl_b32 s54, s61, 9
	s_and_b32 s62, s20, 7
	v_mov_b32_e32 v155, v131
	v_lshl_add_u32 v156, v10, 1, v0
	v_mov_b32_e32 v157, v131
	s_mov_b32 s90, -1
	s_mov_b64 s[72:73], 0x100
	v_add_u32_e32 v137, s64, v175
	v_add_u32_e32 v177, s65, v175
	v_add_u32_e32 v178, 16, v2
	s_mov_b32 s74, 0x3b808081
	s_mov_b32 s31, s10
	s_mov_b32 s89, s59
	s_mov_b32 s91, s55
	s_mov_b32 s66, s55
	s_barrier
	s_branch .LBB0_617

.LBB0_768:
	s_add_u32 s6, s78, 0x15300000
	s_addc_u32 s7, s79, 0
	s_add_u32 s12, s78, 0x28440000
	s_addc_u32 s13, s79, 0
	s_add_u32 s36, s78, 0x90800
	s_addc_u32 s37, s79, 0
	s_add_u32 s16, s78, 0x29a40000
	s_addc_u32 s17, s79, 0
	s_add_u32 s34, s78, 0x29b48000
	s_addc_u32 s35, s79, 0
	v_bfe_u32 v16, v8, 4, 2
	s_add_u32 s38, s78, 0x94000
	v_and_b32_e32 v15, 15, v8
	v_lshlrev_b32_e32 v18, 4, v16
	v_lshlrev_b32_e32 v8, 2, v8
	s_mov_b64 s[72:73], 0x80
	s_addc_u32 s56, s79, 0
	s_and_b32 s57, s2, 3
	v_lshl_or_b32 v138, s9, 6, v15
	v_lshl_or_b32 v15, v15, 6, v18
	s_lshl_b32 s1, s9, 13
	v_and_b32_e32 v8, 32, v8
	s_add_i32 m0, s30, 0x18000
	v_lshl_add_u64 v[6:7], v[6:7], 0, s[72:73]
	v_bitop3_b32 v18, v15, s1, v8 bitop3:0xde
	s_lshl_b32 s1, s57, 12
	global_load_lds_dwordx4 v[6:7], off
	v_lshl_add_u64 v[4:5], v[4:5], 0, s[72:73]
	s_add_i32 m0, s30, 0x1a000
	s_add_i32 s58, s30, 0x8000
	s_add_i32 s59, s30, 0xa000
	global_load_lds_dwordx4 v[4:5], off
	v_lshl_add_u64 v[0:1], v[0:1], 0, s[72:73]
	s_mov_b32 m0, s58
	s_add_u32 s14, s92, 0x80080
	global_load_lds_dwordx4 v[0:1], off
	v_lshl_add_u64 v[0:1], v[2:3], 0, s[72:73]
	s_mov_b32 m0, s59
	s_addc_u32 s15, s93, 0
	global_load_lds_dwordx4 v[0:1], off
	s_add_i32 m0, s30, 0x1c000
	v_lshl_add_u64 v[0:1], s[14:15], 0, v[130:131]
	global_load_lds_dwordx4 v[0:1], off
	v_lshl_add_u64 v[0:1], s[14:15], 0, v[134:135]
	s_add_i32 m0, s30, 0x1e000
	s_cmpk_lt_u32 s8, 0x100
	global_load_lds_dwordx4 v[0:1], off
	s_waitcnt vmcnt(8)
	s_barrier
	v_or_b32_e32 v0, 16, v138
	v_ashrrev_i32_e32 v1, 31, v0
	v_lshlrev_b64 v[142:143], 13, v[0:1]
	v_or_b32_e32 v0, 32, v138
	v_ashrrev_i32_e32 v1, 31, v0
	v_lshlrev_b64 v[144:145], 13, v[0:1]
	v_or_b32_e32 v0, 48, v138
	v_ashrrev_i32_e32 v1, 31, v0
	v_lshlrev_b64 v[146:147], 13, v[0:1]
	v_lshlrev_b32_e32 v0, 15, v12
	v_and_b32_e32 v0, 0xffff0000, v0
	v_lshl_add_u32 v0, v13, 12, v0
	v_and_b32_e32 v1, 1, v12
	v_lshl_or_b32 v0, v1, 6, v0
	v_lshl_add_u32 v148, v14, 1, v0
	v_lshlrev_b32_e32 v0, 15, v9
	v_and_b32_e32 v0, 0xffff0000, v0
	s_waitcnt vmcnt(6)
	s_cselect_b64 s[76:77], -1, 0
	s_add_u32 s40, s78, 0x96000
	v_lshl_add_u32 v0, v10, 12, v0
	v_and_b32_e32 v1, 1, v9
	v_lshlrev_b32_e32 v17, 3, v16
	v_bitop3_b32 v159, v15, s1, v8 bitop3:0xde
	v_ashrrev_i32_e32 v139, 31, v138
	s_addc_u32 s41, s79, 0
	v_lshl_or_b32 v0, v1, 6, v0
	s_add_i32 s60, 16, 0x10000
	s_add_i32 s61, 16, 0x14000
	v_readlane_b32 s14, v254, 56
	v_lshl_or_b32 v160, s57, 5, v17
	v_cmp_eq_u32_e64 s[8:9], 0, v16
	v_lshlrev_b64 v[140:141], 13, v[138:139]
	v_mov_b32_e32 v149, v137
	v_lshl_add_u32 v150, v11, 1, v0
	v_mov_b32_e32 v151, v137
	v_add_u32_e32 v139, s60, v159
	v_add_u32_e32 v161, s61, v159
	v_add_u32_e32 v162, 16, v18
	s_movk_i32 s62, 0x2100
	s_mov_b32 s63, 0x100000
	s_mov_b32 s64, 0x200000
	s_mov_b32 s65, 0x300000
	s_mov_b32 s66, 0x400000
	s_mov_b32 s67, 0x500000
	s_mov_b32 s74, 0x600000
	s_mov_b32 s75, 0x700000
	v_mov_b32_e32 v163, 0x358637bd
	v_mbcnt_hi_u32_b32 v164, -1, v185
	s_mov_b32 s2, s14
	s_mov_b32 s96, s3
	s_barrier
	v_readlane_b32 s15, v254, 57
	s_branch .LBB0_771

.LBB0_900:
	s_add_u32 s4, s0, 0x17400000
	s_addc_u32 s5, s1, 0
	s_add_u32 s6, s0, 0x29b48000
	s_addc_u32 s7, s1, 0
	s_lshl_b32 s10, s10, 5
	s_and_b32 s15, s10, 0x60
	s_mov_b64 s[10:11], 0x80
	s_add_i32 m0, s53, 0x18000
	v_lshl_add_u64 v[6:7], v[6:7], 0, s[10:11]
	s_lshl_b32 s13, s12, 13
	s_lshl_b32 s26, s15, 7
	global_load_lds_dwordx4 v[6:7], off
	v_lshl_add_u64 v[4:5], v[4:5], 0, s[10:11]
	s_add_i32 m0, s53, 0x1a000
	s_add_i32 s58, s53, 0x8000
	s_add_i32 s59, s53, 0xa000
	global_load_lds_dwordx4 v[4:5], off
	v_lshl_add_u64 v[0:1], v[0:1], 0, s[10:11]
	s_mov_b32 m0, s58
	s_add_u32 s16, s78, 0x80080
	global_load_lds_dwordx4 v[0:1], off
	v_lshl_add_u64 v[0:1], v[2:3], 0, s[10:11]
	s_mov_b32 m0, s59
	s_addc_u32 s17, s79, 0
	global_load_lds_dwordx4 v[0:1], off
	s_add_i32 m0, s53, 0x1c000
	v_lshl_add_u64 v[0:1], s[16:17], 0, v[130:131]
	global_load_lds_dwordx4 v[0:1], off
	v_lshl_add_u64 v[0:1], s[16:17], 0, v[134:135]
	s_add_i32 m0, s53, 0x1e000
	s_cmpk_lt_u32 s9, 0x100
	global_load_lds_dwordx4 v[0:1], off
	s_waitcnt vmcnt(8)
	s_barrier
	v_lshrrev_b32_e32 v1, 1, v8
	v_and_b32_e32 v1, 24, v1
	v_and_b32_e32 v0, 15, v8
	v_lshlrev_b32_e32 v2, 1, v1
	v_lshl_or_b32 v147, s12, 6, v0
	v_lshl_or_b32 v0, v0, 6, v2
	v_lshlrev_b32_e32 v2, 2, v8
	v_and_b32_e32 v2, 32, v2
	v_bitop3_b32 v3, v0, s13, v2 bitop3:0xde
	v_bitop3_b32 v149, v0, s26, v2 bitop3:0xde
	v_lshlrev_b32_e32 v0, 15, v12
	v_and_b32_e32 v0, 0xffff0000, v0
	v_or_b32_e32 v151, s15, v1
	v_lshl_add_u32 v0, v13, 12, v0
	v_and_b32_e32 v1, 1, v12
	v_lshl_or_b32 v0, v1, 6, v0
	v_lshl_add_u32 v136, v14, 1, v0
	v_lshlrev_b32_e32 v0, 15, v9
	v_and_b32_e32 v0, 0xffff0000, v0
	s_waitcnt vmcnt(6)
	v_lshl_add_u32 v0, v10, 12, v0
	v_and_b32_e32 v1, 1, v9
	v_lshl_or_b32 v0, v1, 6, v0
	s_sext_i32_i16 s65, s8
	s_cselect_b64 s[12:13], -1, 0
	s_ashr_i32 s60, s22, 31
	s_mov_b32 s61, s22
	v_mov_b32_e32 v137, v131
	v_lshl_add_u32 v138, v11, 1, v0
	v_mov_b32_e32 v139, v131
	v_mov_b64_e32 v[140:141], 0x5ac
	v_mov_b64_e32 v[142:143], 0x5ab
	s_add_i32 s62, 16, 0x10000
	s_add_i32 s63, 16, 0x14000
	v_add_u32_e32 v153, 16, v3
	s_movk_i32 s64, 0x2c00
	v_mov_b32_e32 v144, v131
	v_mov_b32_e32 v146, v131
	v_mov_b32_e32 v148, v131
	v_mov_b32_e32 v150, v131
	v_mov_b32_e32 v152, v131
	v_mov_b32_e32 v154, v131
	v_mov_b32_e32 v156, v131
	v_mov_b32_e32 v158, v131
	s_barrier
	s_branch .LBB0_903

.LBB0_1028:
	s_add_u32 s6, s12, 0x15300000
	s_addc_u32 s7, s13, 0
	s_add_u32 s16, s12, 0x28440000
	s_addc_u32 s17, s13, 0
	s_add_u32 s42, s12, 0x91000
	s_addc_u32 s43, s13, 0
	s_add_u32 s26, s12, 0x29a40000
	s_addc_u32 s27, s13, 0
	s_add_u32 s44, s12, 0x29b48000
	s_addc_u32 s45, s13, 0
	v_bfe_u32 v18, v9, 4, 2
	s_add_u32 s46, s12, 0x96800
	v_and_b32_e32 v17, 15, v9
	v_lshlrev_b32_e32 v20, 4, v18
	v_lshlrev_b32_e32 v9, 2, v9
	s_mov_b64 s[30:31], 0x80
	s_addc_u32 s47, s13, 0
	s_and_b32 s82, s10, 3
	v_lshl_or_b32 v138, s11, 6, v17
	v_lshl_or_b32 v17, v17, 6, v20
	s_lshl_b32 s10, s11, 13
	v_and_b32_e32 v9, 32, v9
	s_add_i32 m0, s54, 0x18000
	v_lshl_add_u64 v[6:7], v[6:7], 0, s[30:31]
	v_bitop3_b32 v20, v17, s10, v9 bitop3:0xde
	s_lshl_b32 s10, s82, 12
	global_load_lds_dwordx4 v[6:7], off
	v_lshl_add_u64 v[2:3], v[2:3], 0, s[30:31]
	s_add_i32 m0, s54, 0x1a000
	s_add_i32 s83, s54, 0x8000
	s_add_i32 s84, s54, 0xa000
	v_bitop3_b32 v159, v17, s10, v9 bitop3:0xde
	global_load_lds_dwordx4 v[2:3], off
	v_lshl_add_u64 v[0:1], v[0:1], 0, s[30:31]
	s_mov_b32 m0, s83
	s_add_u32 s10, s8, 0x160080
	global_load_lds_dwordx4 v[0:1], off
	v_lshl_add_u64 v[0:1], v[4:5], 0, s[30:31]
	s_mov_b32 m0, s84
	s_addc_u32 s11, s9, 0
	global_load_lds_dwordx4 v[0:1], off
	s_add_i32 m0, s54, 0x1c000
	v_lshl_add_u64 v[0:1], s[10:11], 0, v[130:131]
	global_load_lds_dwordx4 v[0:1], off
	v_lshl_add_u64 v[0:1], s[10:11], 0, v[134:135]
	s_add_i32 m0, s54, 0x1e000
	s_cmpk_lt_u32 s2, 0x100
	global_load_lds_dwordx4 v[0:1], off
	s_waitcnt vmcnt(8)
	s_barrier
	v_or_b32_e32 v0, 16, v138
	v_ashrrev_i32_e32 v1, 31, v0
	v_lshlrev_b64 v[142:143], 13, v[0:1]
	v_or_b32_e32 v0, 32, v138
	v_ashrrev_i32_e32 v1, 31, v0
	v_lshlrev_b64 v[144:145], 13, v[0:1]
	v_or_b32_e32 v0, 48, v138
	v_ashrrev_i32_e32 v1, 31, v0
	s_cselect_b64 s[34:35], -1, 0
	v_lshlrev_b64 v[146:147], 13, v[0:1]
	s_add_u32 s48, s12, 0x98800
	v_lshrrev_b32_e32 v1, 1, v13
	v_mul_lo_u32 v0, v14, s4
	s_addc_u32 s49, s13, 0
	v_mad_u64_u32 v[0:1], s[12:13], v1, s5, v[0:1]
	v_or_b32_e32 v0, v0, v15
	v_add_lshl_u32 v136, v0, v16, 1
	v_lshrrev_b32_e32 v1, 1, v8
	v_mul_lo_u32 v0, v10, s4
	v_mad_u64_u32 v[0:1], s[4:5], v1, s5, v[0:1]
	s_mov_b64 s[14:15], 0x160080
	s_waitcnt vmcnt(6)
	v_or_b32_e32 v0, v0, v11
	v_lshlrev_b32_e32 v19, 3, v18
	v_ashrrev_i32_e32 v139, 31, v138
	v_lshl_add_u64 v[148:149], v[136:137], 0, s[14:15]
	v_add_lshl_u32 v136, v0, v12, 1
	s_add_i32 s85, 16, 0x10000
	s_add_i32 s86, 16, 0x14000
	v_readlane_b32 s12, v254, 56
	v_lshl_or_b32 v160, s82, 5, v19
	v_cmp_eq_u32_e64 s[10:11], 0, v18
	v_lshlrev_b64 v[140:141], 13, v[138:139]
	v_lshl_add_u64 v[150:151], v[136:137], 0, s[14:15]
	v_add_u32_e32 v139, s85, v159
	v_add_u32_e32 v161, s86, v159
	v_add_u32_e32 v162, 16, v20
	s_movk_i32 s87, 0x2100
	s_mov_b32 s88, 0x100000
	s_mov_b32 s89, 0x200000
	s_mov_b32 s90, 0x300000
	s_mov_b32 s91, 0x400000
	s_mov_b32 s92, 0x500000
	s_mov_b32 s93, 0x600000
	s_mov_b32 s94, 0x700000
	s_mov_b32 s95, 0x800000
	s_mov_b32 s96, 0x900000
	s_mov_b32 s97, 0xa00000
	s_mov_b32 s50, 0xb00000
	s_mov_b32 s51, 0xc00000
	s_mov_b32 s78, 0xd00000
	s_mov_b32 s79, 0xe00000
	s_mov_b32 s80, 0xf00000
	s_mov_b32 s81, 0x1000000
	s_mov_b32 s52, 0x1100000
	s_mov_b32 s4, 0x1200000
	s_mov_b32 s5, 0x1300000
	s_mov_b32 s21, 0x1400000
	s_mov_b32 s24, 0x1500000
	v_mov_b32_e32 v163, 0x358637bd
	v_mbcnt_hi_u32_b32 v164, -1, v185
	s_mov_b32 s2, s12
	s_mov_b32 s25, s3
	s_barrier
	v_readlane_b32 s13, v254, 57
	s_branch .LBB0_1031

.LBB0_1166:
	s_add_u32 s30, s26, 0x17400000
	s_addc_u32 s31, s27, 0
	s_add_u32 s72, s26, 0x18cc0000
	s_addc_u32 s73, s27, 0
	s_add_u32 s10, s26, 0x19d40000
	s_addc_u32 s11, s27, 0
	v_writelane_b32 v254, s10, 48
	v_bfe_u32 v16, v9, 4, 2
	v_and_b32_e32 v15, 15, v9
	v_writelane_b32 v254, s11, 49
	s_add_u32 s10, s26, 0x1adc0000
	s_addc_u32 s11, s27, 0
	v_writelane_b32 v254, s10, 46
	v_lshlrev_b32_e32 v152, 4, v16
	v_lshlrev_b32_e32 v9, 2, v9
	v_writelane_b32 v254, s11, 47
	s_add_u32 s10, s26, 0x1be40000
	s_addc_u32 s11, s27, 0
	v_writelane_b32 v255, s10, 15
	v_readlane_b32 s52, v254, 14
	v_readlane_b32 s54, v254, 16
	v_writelane_b32 v255, s11, 16
	s_add_u32 s10, s26, 0x1cec0000
	s_addc_u32 s11, s27, 0
	v_readlane_b32 s55, v254, 17
	v_readlane_b32 s66, v254, 28
	v_readlane_b32 s67, v254, 29
	v_writelane_b32 v255, s10, 17
	s_mov_b64 s[54:55], s[66:67]
	v_readlane_b32 s61, v254, 23
	v_writelane_b32 v255, s11, 18
	s_add_u32 s10, s54, 0x6000
	s_addc_u32 s11, s55, 0
	s_add_u32 s86, s26, 0x29b48000
	s_mov_b64 s[88:89], 0x80
	v_readlane_b32 s53, v254, 15
	v_readlane_b32 s63, v254, 25
	s_addc_u32 s87, s27, 0
	s_and_b32 s61, s3, 3
	v_lshl_or_b32 v155, s6, 6, v15
	v_lshl_or_b32 v15, v15, 6, v152
	s_lshl_b32 s3, s6, 13
	v_and_b32_e32 v9, 32, v9
	s_add_i32 m0, s96, 0x18000
	v_lshl_add_u64 v[6:7], v[6:7], 0, s[88:89]
	v_bitop3_b32 v17, v15, s3, v9 bitop3:0xde
	s_lshl_b32 s63, s61, 5
	s_lshl_b32 s3, s61, 12
	global_load_lds_dwordx4 v[6:7], off
	v_lshl_add_u64 v[4:5], v[4:5], 0, s[88:89]
	s_add_i32 m0, s96, 0x1a000
	s_add_i32 s53, s96, 0x8000
	s_add_i32 s54, s96, 0xa000
	global_load_lds_dwordx4 v[4:5], off
	v_lshl_add_u64 v[0:1], v[0:1], 0, s[88:89]
	s_mov_b32 m0, s53
	s_add_u32 s6, s0, 0x80080
	global_load_lds_dwordx4 v[0:1], off
	v_lshl_add_u64 v[0:1], v[2:3], 0, s[88:89]
	s_mov_b32 m0, s54
	s_addc_u32 s7, s1, 0
	global_load_lds_dwordx4 v[0:1], off
	s_add_i32 m0, s96, 0x1c000
	v_lshl_add_u64 v[0:1], s[6:7], 0, v[146:147]
	global_load_lds_dwordx4 v[0:1], off
	v_lshl_add_u64 v[0:1], s[6:7], 0, v[150:151]
	s_add_i32 m0, s96, 0x1e000
	v_writelane_b32 v255, s10, 19
	global_load_lds_dwordx4 v[0:1], off
	s_waitcnt vmcnt(8)
	s_barrier
	s_nop 0
	v_writelane_b32 v255, s11, 20
	v_bitop3_b32 v157, v15, s3, v9 bitop3:0xde
	s_cmpk_lt_u32 s2, 0x100
	v_cmp_eq_u32_e64 s[2:3], 0, v16
	v_readlane_b32 s64, v254, 26
	s_cselect_b64 s[90:91], -1, 0
	v_writelane_b32 v255, s2, 21
	s_lshl_b32 s55, s61, 6
	s_ashr_i32 s64, s20, 31
	v_writelane_b32 v255, s3, 22
	s_ashr_i32 s2, s22, 31
	s_lshl_b32 s5, s61, 7
	v_lshlrev_b32_e32 v154, 3, v16
	s_add_u32 s6, s26, s5
	v_or_b32_e32 v0, s63, v154
	s_addc_u32 s7, s27, 0
	v_or_b32_e32 v175, 0xffffe600, v0
	v_or_b32_e32 v156, s55, v154
	v_lshl_add_u64 v[0:1], s[6:7], 0, v[152:153]
	s_mov_b64 s[6:7], 0x188a0000
	v_lshl_add_u64 v[158:159], v[0:1], 0, s[6:7]
	s_mov_b64 s[6:7], 0x18480000
	v_lshlrev_b32_e32 v152, 2, v156
	v_lshl_add_u64 v[160:161], v[0:1], 0, s[6:7]
	v_lshl_add_u64 v[0:1], s[68:69], 0, v[152:153]
	s_mov_b64 s[6:7], 0x4350000
	v_lshl_add_u64 v[162:163], v[0:1], 0, s[6:7]
	s_mov_b64 s[6:7], 0x4310000
	v_lshl_add_u64 v[164:165], v[0:1], 0, s[6:7]
	v_lshlrev_b32_e32 v0, 15, v12
	v_and_b32_e32 v0, 0xffff0000, v0
	v_lshl_add_u32 v0, v13, 12, v0
	v_and_b32_e32 v1, 1, v12
	v_lshl_or_b32 v0, v1, 6, v0
	v_readlane_b32 s65, v254, 27
	v_lshl_add_u32 v166, v14, 1, v0
	v_lshlrev_b32_e32 v0, 15, v8
	s_add_u32 s65, s68, 0x4200000
	v_and_b32_e32 v0, 0xffff0000, v0
	s_waitcnt vmcnt(6)
	s_addc_u32 s82, s69, 0
	v_lshl_add_u32 v0, v10, 12, v0
	v_and_b32_e32 v1, 1, v8
	v_readlane_b32 s62, v254, 24
	s_add_u32 s83, s68, 0x4100000
	v_lshl_or_b32 v0, v1, 6, v0
	s_mov_b32 s40, 0xffea0000
	s_mov_b32 s93, 0
	s_mov_b32 s3, s22
	s_addc_u32 s66, s69, 0
	v_mov_b32_e32 v167, v153
	v_lshl_add_u32 v168, v11, 1, v0
	v_mov_b32_e32 v169, v153
	v_mov_b64_e32 v[170:171], 0x672
	v_mov_b64_e32 v[172:173], 0x671
	s_add_i32 s21, 16, 0x10000
	s_add_i32 s33, 16, 0x14000
	v_add_u32_e32 v177, 16, v17
	s_mov_b32 s94, 0x437f0000
	v_mov_b32_e32 v179, 0x358637bd
	s_mov_b32 s67, 0x800000
	v_mbcnt_hi_u32_b32 v181, -1, v185
	v_mov_b32_e32 v187, 0x3e000000
	s_mov_b32 s62, 0
	v_mov_b32_e32 v174, v153
	v_mov_b32_e32 v176, v153
	v_mov_b32_e32 v178, v153
	v_mov_b32_e32 v180, v153
	v_mov_b32_e32 v182, v153
	v_mov_b32_e32 v184, v153
	v_mov_b32_e32 v186, v153
	v_mov_b32_e32 v188, v153
	s_mov_b32 s41, -1
	v_readlane_b32 s56, v254, 18
	v_readlane_b32 s57, v254, 19
	v_readlane_b32 s58, v254, 20
	v_readlane_b32 s59, v254, 21
	v_readlane_b32 s60, v254, 22
	s_barrier
	s_branch .LBB0_1169

.LBB0_1457:
	s_lshl_b32 s43, s43, 5
	s_and_b32 s47, s43, 0x60
	s_add_i32 m0, s74, 0x18000
	v_lshl_add_u64 v[6:7], v[6:7], 0, s[30:31]
	s_lshl_b32 s46, s42, 13
	s_lshl_b32 s43, s47, 7
	global_load_lds_dwordx4 v[6:7], off
	v_lshl_add_u64 v[4:5], v[4:5], 0, s[30:31]
	s_add_i32 m0, s74, 0x1a000
	s_add_i32 s78, s74, 0x8000
	s_add_i32 s79, s74, 0xa000
	global_load_lds_dwordx4 v[4:5], off
	v_lshl_add_u64 v[0:1], v[0:1], 0, s[30:31]
	s_mov_b32 m0, s78
	s_add_u32 s44, s8, 0x40080
	global_load_lds_dwordx4 v[0:1], off
	v_lshl_add_u64 v[0:1], v[2:3], 0, s[30:31]
	s_mov_b32 m0, s79
	s_addc_u32 s45, s9, 0
	global_load_lds_dwordx4 v[0:1], off
	s_add_i32 m0, s74, 0x1c000
	v_lshl_add_u64 v[0:1], s[44:45], 0, v[144:145]
	global_load_lds_dwordx4 v[0:1], off
	v_lshl_add_u64 v[0:1], s[44:45], 0, v[146:147]
	s_add_i32 m0, s74, 0x1e000
	s_cmpk_lt_u32 s4, 0x100
	global_load_lds_dwordx4 v[0:1], off
	s_waitcnt vmcnt(8)
	s_barrier
	v_lshrrev_b32_e32 v1, 1, v12
	v_and_b32_e32 v1, 24, v1
	v_and_b32_e32 v0, 15, v12
	v_lshlrev_b32_e32 v2, 1, v1
	v_lshl_or_b32 v152, s42, 6, v0
	v_lshl_or_b32 v0, v0, 6, v2
	v_lshlrev_b32_e32 v2, 2, v12
	v_and_b32_e32 v2, 32, v2
	v_bitop3_b32 v4, v0, s46, v2 bitop3:0xde
	v_bitop3_b32 v184, v0, s43, v2 bitop3:0xde
	v_or_b32_e32 v0, 16, v152
	v_or_b32_e32 v186, s47, v1
	v_ashrrev_i32_e32 v1, 31, v0
	v_lshlrev_b64 v[156:157], 13, v[0:1]
	v_or_b32_e32 v0, 32, v152
	v_ashrrev_i32_e32 v1, 31, v0
	v_lshlrev_b64 v[158:159], 13, v[0:1]
	v_or_b32_e32 v0, 48, v152
	v_ashrrev_i32_e32 v1, 31, v0
	v_add_u32_e32 v2, 0x2000, v152
	v_lshlrev_b64 v[160:161], 13, v[0:1]
	v_mov_b64_e32 v[0:1], s[0:1]
	s_cselect_b64 s[42:43], -1, 0
	v_add_u32_e32 v5, 0x2010, v152
	s_lshl_b32 s4, s38, 11
	v_mad_i64_i32 v[2:3], s[48:49], v2, s17, v[0:1]
	v_add_u32_e32 v6, 0x2020, v152
	v_add_u32_e32 v7, 0x2030, v152
	v_lshl_add_u64 v[162:163], v[2:3], 0, s[4:5]
	v_mad_i64_i32 v[2:3], s[48:49], v5, s17, v[0:1]
	v_lshl_add_u64 v[164:165], v[2:3], 0, s[4:5]
	v_mad_i64_i32 v[2:3], s[48:49], v6, s17, v[0:1]
	v_mad_i64_i32 v[0:1], s[48:49], v7, s17, v[0:1]
	v_lshl_add_u64 v[168:169], v[0:1], 0, s[4:5]
	v_lshlrev_b32_e32 v0, 14, v8
	v_and_b32_e32 v0, 0xffff8000, v0
	v_lshl_add_u32 v0, v9, 11, v0
	v_and_b32_e32 v1, 1, v8
	v_lshl_or_b32 v0, v1, 6, v0
	v_lshl_add_u32 v170, v10, 1, v0
	v_lshlrev_b32_e32 v0, 14, v13
	v_and_b32_e32 v0, 0xffff8000, v0
	s_waitcnt vmcnt(6)
	s_cmp_lg_u32 s38, 0
	v_lshl_add_u32 v0, v11, 11, v0
	v_and_b32_e32 v1, 1, v13
	v_ashrrev_i32_e32 v153, 31, v152
	s_cselect_b64 s[44:45], -1, 0
	s_add_u32 s46, s0, s4
	v_lshl_or_b32 v0, v1, 6, v0
	v_readlane_b32 s48, v254, 56
	v_lshlrev_b64 v[154:155], 13, v[152:153]
	s_mov_b32 s80, 0
	s_addc_u32 s47, s1, 0
	s_lshl_b32 s81, s38, 2
	v_lshl_add_u64 v[166:167], v[2:3], 0, s[4:5]
	v_mov_b32_e32 v171, v145
	v_lshl_add_u32 v172, v14, 1, v0
	v_mov_b32_e32 v173, v145
	v_add_u32_e32 v153, 16, v4
	s_mov_b32 s85, s14
	s_mov_b32 s84, s16
	s_mov_b32 s86, s52
	s_mov_b32 s4, s48
	s_barrier
	v_readlane_b32 s49, v254, 57
	s_branch .LBB0_1460

.LBB0_1549:
	s_lshl_b32 s16, s16, 5
	s_and_b32 s30, s16, 0x60
	s_mov_b64 s[16:17], 0x80
	s_add_i32 m0, s13, 0x18000
	v_lshl_add_u64 v[6:7], v[6:7], 0, s[16:17]
	s_lshl_b32 s27, s26, 13
	s_lshl_b32 s31, s30, 7
	global_load_lds_dwordx4 v[6:7], off
	v_lshl_add_u64 v[4:5], v[4:5], 0, s[16:17]
	s_add_i32 m0, s13, 0x1a000
	s_add_i32 s55, s13, 0x8000
	s_add_i32 s56, s13, 0xa000
	global_load_lds_dwordx4 v[4:5], off
	v_lshl_add_u64 v[0:1], v[0:1], 0, s[16:17]
	s_mov_b32 m0, s55
	s_add_u32 s28, s4, 0x40080
	global_load_lds_dwordx4 v[0:1], off
	v_lshl_add_u64 v[0:1], v[2:3], 0, s[16:17]
	s_mov_b32 m0, s56
	s_addc_u32 s29, s5, 0
	global_load_lds_dwordx4 v[0:1], off
	s_add_i32 m0, s13, 0x1c000
	v_lshl_add_u64 v[0:1], s[28:29], 0, v[130:131]
	global_load_lds_dwordx4 v[0:1], off
	v_lshl_add_u64 v[0:1], s[28:29], 0, v[134:135]
	s_add_i32 m0, s13, 0x1e000
	s_movk_i32 s61, 0x1800
	global_load_lds_dwordx4 v[0:1], off
	s_waitcnt vmcnt(8)
	s_barrier
	v_lshrrev_b32_e32 v1, 1, v12
	v_and_b32_e32 v1, 24, v1
	v_and_b32_e32 v0, 15, v12
	v_lshlrev_b32_e32 v2, 1, v1
	v_lshl_or_b32 v136, s26, 6, v0
	v_lshl_or_b32 v0, v0, 6, v2
	v_lshlrev_b32_e32 v2, 2, v12
	v_and_b32_e32 v2, 32, v2
	v_bitop3_b32 v175, v0, s31, v2 bitop3:0xde
	v_bitop3_b32 v2, v0, s27, v2 bitop3:0xde
	v_or_b32_e32 v0, 16, v136
	v_or_b32_e32 v176, s30, v1
	v_ashrrev_i32_e32 v1, 31, v0
	v_lshlrev_b64 v[140:141], 13, v[0:1]
	v_or_b32_e32 v0, 32, v136
	v_ashrrev_i32_e32 v1, 31, v0
	v_lshlrev_b64 v[142:143], 13, v[0:1]
	v_or_b32_e32 v0, 48, v136
	v_ashrrev_i32_e32 v1, 31, v0
	v_add_u32_e32 v3, 0x2000, v136
	v_add_u32_e32 v4, 0x2010, v136
	v_add_u32_e32 v5, 0x2020, v136
	v_add_u32_e32 v6, 0x2030, v136
	v_lshlrev_b64 v[144:145], 13, v[0:1]
	v_mov_b64_e32 v[0:1], s[0:1]
	s_sext_i32_i8 s57, s2
	s_cmpk_lt_u32 s3, 0x100
	v_mad_i64_i32 v[146:147], s[2:3], v3, s61, v[0:1]
	v_mad_i64_i32 v[148:149], s[2:3], v4, s61, v[0:1]
	v_mad_i64_i32 v[150:151], s[2:3], v5, s61, v[0:1]
	v_mad_i64_i32 v[152:153], s[2:3], v6, s61, v[0:1]
	v_lshlrev_b32_e32 v0, 14, v11
	v_and_b32_e32 v0, 0xffff8000, v0
	v_lshl_add_u32 v0, v13, 11, v0
	v_and_b32_e32 v1, 1, v11
	v_lshl_or_b32 v0, v1, 6, v0
	v_lshl_add_u32 v154, v14, 1, v0
	v_lshlrev_b32_e32 v0, 14, v8
	v_and_b32_e32 v0, 0xffff8000, v0
	s_waitcnt vmcnt(6)
	s_cselect_b64 s[26:27], -1, 0
	s_cmpk_lt_i32 s20, 0x60
	v_lshl_add_u32 v0, v9, 11, v0
	v_and_b32_e32 v1, 1, v8
	v_ashrrev_i32_e32 v137, 31, v136
	s_cselect_b64 s[28:29], -1, 0
	s_bfe_u32 s59, s20, 0x20003
	s_mov_b32 s31, 0
	v_lshl_or_b32 v0, v1, 6, v0
	s_add_i32 s62, 16, 0x10000
	s_add_i32 s63, 16, 0x14000
	v_lshlrev_b64 v[138:139], 13, v[136:137]
	s_ashr_i32 s58, s20, 5
	s_lshl_b32 s30, s59, 9
	s_and_b32 s60, s20, 7
	v_mov_b32_e32 v155, v131
	v_lshl_add_u32 v156, v10, 1, v0
	v_mov_b32_e32 v157, v131
	s_mov_b32 s72, -1
	s_mov_b64 s[34:35], 0x100
	v_add_u32_e32 v137, s62, v175
	v_add_u32_e32 v177, s63, v175
	v_add_u32_e32 v178, 16, v2
	s_mov_b32 s36, 0x3b808081
	s_mov_b32 s75, s12
	s_mov_b32 s67, s57
	s_mov_b32 s73, s31
	s_mov_b32 s64, s31
	s_cmpk_lt_i32 s20, 0x60
	s_cselect_b32 s75, 32, s75
	s_cselect_b32 s67, s60, s67
	s_cselect_b32 s74, 4, s74
	s_cselect_b32 s72, s59, s72
	s_cselect_b32 s73, s58, s73
	s_barrier
	s_branch .LBB0_1552

.LBB0_1701:
	s_add_u32 s12, s34, 0x15300000
	s_addc_u32 s13, s35, 0
	s_add_u32 s14, s34, 0x28440000
	s_addc_u32 s15, s35, 0
	s_add_u32 s57, s34, 0x92000
	s_addc_u32 s58, s35, 0
	s_add_u32 s16, s34, 0x29a40000
	s_addc_u32 s17, s35, 0
	s_add_u32 s26, s34, 0x29b48000
	s_addc_u32 s27, s35, 0
	s_add_u32 s59, s34, 0x99000
	s_mov_b64 s[28:29], 0x80
	s_addc_u32 s60, s35, 0
	s_and_b32 s61, s3, 3
	s_add_i32 m0, s53, 0x18000
	v_lshl_add_u64 v[6:7], v[6:7], 0, s[28:29]
	s_lshl_b32 s1, s6, 13
	s_lshl_b32 s3, s61, 12
	global_load_lds_dwordx4 v[6:7], off
	v_lshl_add_u64 v[4:5], v[4:5], 0, s[28:29]
	s_add_i32 m0, s53, 0x1a000
	s_add_i32 s62, s53, 0x8000
	s_add_i32 s63, s53, 0xa000
	global_load_lds_dwordx4 v[4:5], off
	v_lshl_add_u64 v[0:1], v[0:1], 0, s[28:29]
	s_mov_b32 m0, s62
	s_add_u32 s30, s8, 0x80080
	global_load_lds_dwordx4 v[0:1], off
	v_lshl_add_u64 v[0:1], v[2:3], 0, s[28:29]
	s_mov_b32 m0, s63
	s_addc_u32 s31, s9, 0
	global_load_lds_dwordx4 v[0:1], off
	s_add_i32 m0, s53, 0x1c000
	v_lshl_add_u64 v[0:1], s[30:31], 0, v[130:131]
	global_load_lds_dwordx4 v[0:1], off
	v_lshl_add_u64 v[0:1], s[30:31], 0, v[134:135]
	s_add_i32 m0, s53, 0x1e000
	s_cmpk_lt_u32 s2, 0x100
	global_load_lds_dwordx4 v[0:1], off
	s_waitcnt vmcnt(8)
	s_barrier
	v_bfe_u32 v1, v8, 4, 2
	v_and_b32_e32 v0, 15, v8
	v_lshlrev_b32_e32 v3, 4, v1
	v_lshl_or_b32 v138, s6, 6, v0
	v_lshl_or_b32 v0, v0, 6, v3
	v_lshlrev_b32_e32 v3, 2, v8
	v_and_b32_e32 v3, 32, v3
	v_bitop3_b32 v4, v0, s1, v3 bitop3:0xde
	v_bitop3_b32 v159, v0, s3, v3 bitop3:0xde
	v_or_b32_e32 v0, 16, v138
	v_lshlrev_b32_e32 v2, 3, v1
	v_cmp_eq_u32_e64 s[2:3], 0, v1
	v_ashrrev_i32_e32 v1, 31, v0
	v_lshlrev_b64 v[142:143], 13, v[0:1]
	v_or_b32_e32 v0, 32, v138
	v_ashrrev_i32_e32 v1, 31, v0
	v_lshlrev_b64 v[144:145], 13, v[0:1]
	v_or_b32_e32 v0, 48, v138
	v_ashrrev_i32_e32 v1, 31, v0
	v_lshlrev_b64 v[146:147], 13, v[0:1]
	v_lshlrev_b32_e32 v0, 15, v12
	v_and_b32_e32 v0, 0xffff0000, v0
	v_lshl_add_u32 v0, v13, 12, v0
	v_and_b32_e32 v1, 1, v12
	v_lshl_or_b32 v0, v1, 6, v0
	v_lshl_add_u32 v148, v14, 1, v0
	v_lshlrev_b32_e32 v0, 15, v9
	v_and_b32_e32 v0, 0xffff0000, v0
	s_waitcnt vmcnt(6)
	s_cselect_b64 s[30:31], -1, 0
	s_add_u32 s34, s34, 0x9b000
	v_lshl_add_u32 v0, v10, 12, v0
	v_and_b32_e32 v1, 1, v9
	v_ashrrev_i32_e32 v139, 31, v138
	s_addc_u32 s35, s35, 0
	v_lshl_or_b32 v0, v1, 6, v0
	s_add_i32 s64, 16, 0x10000
	s_add_i32 s65, 16, 0x14000
	v_readlane_b32 s36, v254, 56
	v_lshl_or_b32 v160, s61, 5, v2
	v_lshlrev_b64 v[140:141], 13, v[138:139]
	v_mov_b32_e32 v149, v137
	v_lshl_add_u32 v150, v11, 1, v0
	v_mov_b32_e32 v151, v137
	v_add_u32_e32 v139, s64, v159
	v_add_u32_e32 v161, s65, v159
	v_add_u32_e32 v162, 16, v4
	s_movk_i32 s66, 0x2100
	s_mov_b32 s67, 0x100000
	s_mov_b32 s72, 0x200000
	s_mov_b32 s73, 0x300000
	s_mov_b32 s74, 0x400000
	s_mov_b32 s75, 0x500000
	s_mov_b32 s76, 0x600000
	s_mov_b32 s77, 0x700000
	v_mov_b32_e32 v163, 0x358637bd
	v_mbcnt_hi_u32_b32 v164, -1, v185
	s_mov_b32 s6, s36
	s_mov_b32 s78, s7
	s_barrier
	v_readlane_b32 s37, v254, 57
	s_branch .LBB0_1704

.LBB0_1833:
	s_add_u32 s4, s2, 0x17400000
	s_addc_u32 s5, s3, 0
	s_add_u32 s6, s2, 0x29b48000
	s_addc_u32 s7, s3, 0
	s_lshl_b32 s2, s10, 5
	s_mov_b64 s[10:11], 0x80
	s_and_b32 s15, s2, 0x60
	s_add_i32 m0, s38, 0x18000
	v_lshl_add_u64 v[6:7], v[6:7], 0, s[10:11]
	s_lshl_b32 s9, s14, 13
	s_lshl_b32 s16, s15, 7
	global_load_lds_dwordx4 v[6:7], off
	v_lshl_add_u64 v[4:5], v[4:5], 0, s[10:11]
	s_add_i32 m0, s38, 0x1a000
	s_add_i32 s43, s38, 0x8000
	s_add_i32 s44, s38, 0xa000
	global_load_lds_dwordx4 v[4:5], off
	v_lshl_add_u64 v[0:1], v[0:1], 0, s[10:11]
	s_mov_b32 m0, s43
	s_add_u32 s2, s30, 0x80080
	global_load_lds_dwordx4 v[0:1], off
	v_lshl_add_u64 v[0:1], v[2:3], 0, s[10:11]
	s_mov_b32 m0, s44
	s_addc_u32 s3, s31, 0
	global_load_lds_dwordx4 v[0:1], off
	s_add_i32 m0, s38, 0x1c000
	v_lshl_add_u64 v[0:1], s[2:3], 0, v[130:131]
	global_load_lds_dwordx4 v[0:1], off
	v_lshl_add_u64 v[0:1], s[2:3], 0, v[134:135]
	s_add_i32 m0, s38, 0x1e000
	s_cmpk_lt_u32 s13, 0x100
	global_load_lds_dwordx4 v[0:1], off
	s_waitcnt vmcnt(8)
	s_barrier
	v_lshrrev_b32_e32 v1, 1, v8
	v_and_b32_e32 v1, 24, v1
	v_and_b32_e32 v0, 15, v8
	v_lshlrev_b32_e32 v2, 1, v1
	v_lshl_or_b32 v145, s14, 6, v0
	v_lshl_or_b32 v0, v0, 6, v2
	v_lshlrev_b32_e32 v2, 2, v8
	v_and_b32_e32 v2, 32, v2
	v_bitop3_b32 v3, v0, s9, v2 bitop3:0xde
	v_bitop3_b32 v147, v0, s16, v2 bitop3:0xde
	v_lshlrev_b32_e32 v0, 15, v12
	v_and_b32_e32 v0, 0xffff0000, v0
	v_or_b32_e32 v149, s15, v1
	v_lshl_add_u32 v0, v13, 12, v0
	v_and_b32_e32 v1, 1, v12
	v_lshl_or_b32 v0, v1, 6, v0
	v_lshl_add_u32 v136, v14, 1, v0
	v_lshlrev_b32_e32 v0, 15, v9
	v_and_b32_e32 v0, 0xffff0000, v0
	s_waitcnt vmcnt(6)
	v_lshl_add_u32 v0, v10, 12, v0
	v_and_b32_e32 v1, 1, v9
	v_lshl_or_b32 v0, v1, 6, v0
	s_sext_i32_i16 s50, s12
	s_cselect_b64 s[12:13], -1, 0
	s_ashr_i32 s45, s22, 31
	s_mov_b32 s46, s22
	v_mov_b32_e32 v137, v131
	v_lshl_add_u32 v138, v11, 1, v0
	v_mov_b32_e32 v139, v131
	v_mov_b64_e32 v[140:141], 0x5ac
	v_mov_b64_e32 v[142:143], 0x5ab
	s_add_i32 s47, 16, 0x10000
	s_add_i32 s48, 16, 0x14000
	v_add_u32_e32 v151, 16, v3
	s_movk_i32 s49, 0x2c00
	v_mov_b32_e32 v144, v131
	v_mov_b32_e32 v146, v131
	v_mov_b32_e32 v148, v131
	v_mov_b32_e32 v150, v131
	v_mov_b32_e32 v152, v131
	v_mov_b32_e32 v154, v131
	v_mov_b32_e32 v156, v131
	v_mov_b32_e32 v158, v131
	s_barrier
	s_branch .LBB0_1836

.LBB0_1913:
	s_add_u32 s4, s70, 0x15300000
	s_addc_u32 s5, s71, 0
	s_add_u32 s6, s70, 0x28440000
	s_addc_u32 s7, s71, 0
	s_add_u32 s51, s70, 0x92800
	v_and_b32_e32 v17, 15, v8
	s_addc_u32 s52, s71, 0
	s_and_b32 s13, s8, 3
	v_lshl_or_b32 v136, s9, 6, v17
	s_lshl_b32 s14, s9, 13
	s_mov_b64 s[8:9], 0x80
	s_add_i32 m0, s46, 0x18000
	v_lshl_add_u64 v[6:7], v[6:7], 0, s[8:9]
	s_lshl_b32 s15, s13, 12
	global_load_lds_dwordx4 v[6:7], off
	v_lshl_add_u64 v[2:3], v[2:3], 0, s[8:9]
	s_add_i32 m0, s46, 0x1a000
	s_add_i32 s53, s46, 0x8000
	s_add_i32 s54, s46, 0xa000
	global_load_lds_dwordx4 v[2:3], off
	v_lshl_add_u64 v[0:1], v[0:1], 0, s[8:9]
	s_mov_b32 m0, s53
	s_add_u32 s10, s38, 0x160080
	global_load_lds_dwordx4 v[0:1], off
	v_lshl_add_u64 v[0:1], v[4:5], 0, s[8:9]
	s_mov_b32 m0, s54
	s_addc_u32 s11, s39, 0
	global_load_lds_dwordx4 v[0:1], off
	s_add_i32 m0, s46, 0x1c000
	v_lshl_add_u64 v[0:1], s[10:11], 0, v[130:131]
	global_load_lds_dwordx4 v[0:1], off
	v_lshl_add_u64 v[0:1], s[10:11], 0, v[134:135]
	s_add_i32 m0, s46, 0x1e000
	v_bfe_u32 v18, v8, 4, 2
	global_load_lds_dwordx4 v[0:1], off
	s_waitcnt vmcnt(8)
	s_barrier
	v_lshlrev_b32_e32 v19, 3, v18
	v_lshlrev_b32_e32 v18, 4, v18
	v_lshlrev_b32_e32 v0, 2, v8
	v_lshl_or_b32 v17, v17, 6, v18
	v_and_b32_e32 v0, 32, v0
	v_bitop3_b32 v2, v17, s14, v0 bitop3:0xde
	v_bitop3_b32 v157, v17, s15, v0 bitop3:0xde
	v_or_b32_e32 v0, 16, v136
	v_ashrrev_i32_e32 v1, 31, v0
	v_lshlrev_b64 v[140:141], 13, v[0:1]
	v_or_b32_e32 v0, 32, v136
	v_ashrrev_i32_e32 v1, 31, v0
	v_lshlrev_b64 v[142:143], 13, v[0:1]
	v_or_b32_e32 v0, 48, v136
	v_ashrrev_i32_e32 v1, 31, v0
	v_lshlrev_b64 v[144:145], 13, v[0:1]
	v_lshrrev_b32_e32 v1, 1, v13
	v_mul_lo_u32 v0, v14, s3
	v_mad_u64_u32 v[0:1], s[16:17], v1, s12, v[0:1]
	v_or_b32_e32 v0, v0, v15
	s_mov_b64 s[14:15], 0x160080
	v_add_lshl_u32 v0, v0, v16, 1
	v_mov_b32_e32 v1, v131
	v_lshl_add_u64 v[146:147], v[0:1], 0, s[14:15]
	v_lshrrev_b32_e32 v1, 1, v9
	v_mul_lo_u32 v0, v10, s3
	s_cmpk_lt_u32 s2, 0x100
	v_mad_u64_u32 v[0:1], s[2:3], v1, s12, v[0:1]
	s_waitcnt vmcnt(6)
	v_or_b32_e32 v0, v0, v11
	v_readlane_b32 s2, v254, 56
	s_cselect_b64 s[10:11], -1, 0
	v_ashrrev_i32_e32 v137, 31, v136
	v_add_lshl_u32 v0, v0, v12, 1
	v_mov_b32_e32 v1, v131
	s_add_i32 s55, 16, 0x10000
	s_add_i32 s56, 16, 0x14000
	v_readlane_b32 s3, v254, 57
	v_lshl_or_b32 v158, s13, 5, v19
	v_lshlrev_b64 v[138:139], 13, v[136:137]
	v_lshl_add_u64 v[148:149], v[0:1], 0, s[14:15]
	v_add_u32_e32 v137, s55, v157
	v_add_u32_e32 v159, s56, v157
	v_add_u32_e32 v160, 16, v2
	s_movk_i32 s57, 0x2080
	s_mov_b64 s[12:13], 0x40000
	s_movk_i32 s58, 0x1ff0
	s_mov_b64 s[14:15], 0x48000
	s_movk_i32 s59, 0x1fe0
	s_mov_b64 s[16:17], 0x50000
	s_movk_i32 s60, 0x1fd0
	s_mov_b64 s[24:25], 0x58000
	s_mov_b64 s[26:27], 0x1000000
	s_mov_b32 s61, 0x100000
	s_mov_b32 s62, 0x200000
	s_mov_b32 s63, 0x300000
	s_mov_b32 s64, 0x400000
	s_mov_b32 s65, 0x500000
	s_mov_b32 s66, 0x600000
	s_mov_b32 s67, 0x700000
	s_mov_b32 s70, 0x800000
	s_mov_b32 s71, 0x900000
	s_mov_b32 s72, 0xa00000
	s_mov_b32 s73, 0xb00000
	s_mov_b32 s74, 0xc00000
	s_mov_b32 s75, 0xd00000
	s_mov_b32 s76, 0xe00000
	s_mov_b32 s77, 0xf00000
	s_mov_b32 s78, 0x1000000
	s_mov_b32 s79, 0x1100000
	s_mov_b32 s80, 0x1200000
	s_mov_b32 s81, 0x1300000
	s_mov_b32 s82, 0x1400000
	s_mov_b32 s83, 0x1500000
	s_mov_b32 s84, s3
	s_barrier
	s_branch .LBB0_1916
